# ret_sample: wave 0's serial A8 loop moved behind its first 12 row/v loads (registers renamed), so it no longer trails the other waves by the loop's length in every item
# speedup vs baseline: 1.0041x; 1.0022x over previous
.LBB0_1339:
	s_lshl_b32 s1, s0, 1
	s_and_b32 s27, s1, -8
	s_waitcnt vmcnt(30)
	v_add_u32_e32 v6, 0x200, v152
	s_addk_i32 s27, 0x4000
	v_ashrrev_i32_e32 v1, 8, v152
	s_waitcnt vmcnt(28)
	v_ashrrev_i32_e32 v15, 8, v6
	v_add_u32_e32 v10, 0x400, v152
	v_add_u32_e32 v2, s27, v1
	v_add_u32_e32 v6, s27, v15
	s_waitcnt vmcnt(27)
	v_ashrrev_i32_e32 v16, 8, v10
	v_ashrrev_i32_e32 v3, 31, v2
	v_lshlrev_b32_sdwa v4, v204, v152 dst_sel:DWORD dst_unused:UNUSED_PAD src0_sel:DWORD src1_sel:BYTE_0
	v_ashrrev_i32_e32 v7, 31, v6
	v_add_u32_e32 v10, s27, v16
	v_lshlrev_b64 v[2:3], 11, v[2:3]
	v_lshl_or_b32 v14, s10, 9, v4
	v_lshlrev_b64 v[6:7], 11, v[6:7]
	v_ashrrev_i32_e32 v11, 31, v10
	v_or_b32_e32 v2, v2, v14
	v_or_b32_e32 v6, v6, v14
	v_lshlrev_b64 v[10:11], 11, v[10:11]
	v_lshl_add_u64 v[4:5], s[30:31], 0, v[2:3]
	v_lshl_add_u64 v[8:9], s[30:31], 0, v[6:7]
	v_lshl_add_u64 v[6:7], s[34:35], 0, v[6:7]
	v_or_b32_e32 v10, v10, v14
	v_lshl_add_u64 v[2:3], s[34:35], 0, v[2:3]
	v_lshl_add_u64 v[12:13], s[30:31], 0, v[10:11]
	global_load_ushort v17, v[4:5], off
	global_load_ushort v18, v[2:3], off
	s_nop 0
	global_load_ushort v8, v[8:9], off
	s_nop 0
	global_load_ushort v6, v[6:7], off
	s_nop 0
	global_load_ushort v7, v[12:13], off
	v_lshl_add_u64 v[2:3], s[34:35], 0, v[10:11]
	global_load_ushort v9, v[2:3], off
	v_add_u32_e32 v2, 0x600, v152
	v_ashrrev_i32_e32 v10, 8, v2
	v_add_u32_e32 v2, s27, v10
	v_ashrrev_i32_e32 v3, 31, v2
	v_lshlrev_b64 v[2:3], 11, v[2:3]
	v_or_b32_e32 v2, v2, v14
	v_lshl_add_u64 v[4:5], s[30:31], 0, v[2:3]
	global_load_ushort v4, v[4:5], off
	v_lshl_add_u64 v[2:3], s[34:35], 0, v[2:3]
	global_load_ushort v2, v[2:3], off
	v_lshlrev_b32_sdwa v3, v203, v152 dst_sel:DWORD dst_unused:UNUSED_PAD src0_sel:DWORD src1_sel:BYTE_0
	v_add_u32_e32 v5, 1, v1
	v_add_u32_e32 v11, v3, v1
	v_sub_u32_e32 v1, 7, v1
	v_cvt_f32_i32_e32 v5, v5
	v_cvt_f32_i32_e32 v1, v1
	v_add_u32_e32 v12, 1, v15
	v_sub_u32_e32 v14, 7, v15
	v_cvt_f32_i32_e32 v12, v12
	v_cvt_f32_i32_e32 v14, v14
	v_add_u32_e32 v13, v15, v3
	v_add_u32_e32 v15, 1, v16
	v_add_u32_e32 v19, v16, v3
	v_sub_u32_e32 v16, 7, v16
	v_mul_f32_e32 v5, v0, v5
	v_mul_f32_e32 v1, v0, v1
	v_cvt_f32_i32_e32 v16, v16
	v_mul_f32_e32 v5, 0x3fb8aa3b, v5
	v_mul_f32_e32 v1, 0x3fb8aa3b, v1
	v_mul_f32_e32 v12, v0, v12
	v_mul_f32_e32 v14, v0, v14
	v_exp_f32_e32 v5, v5
	v_exp_f32_e32 v1, v1
	v_mul_f32_e32 v12, 0x3fb8aa3b, v12
	v_mul_f32_e32 v14, 0x3fb8aa3b, v14
	v_exp_f32_e32 v12, v12
	v_exp_f32_e32 v14, v14
	v_cvt_f32_i32_e32 v15, v15
	v_mul_f32_e32 v16, v0, v16
	v_lshl_add_u32 v11, v11, 2, 0
	v_mul_f32_e32 v16, 0x3fb8aa3b, v16
	v_lshl_add_u32 v13, v13, 2, 0
	v_mul_f32_e32 v15, v0, v15
	v_mul_f32_e32 v15, 0x3fb8aa3b, v15
	v_exp_f32_e32 v15, v15
	v_add_u32_e32 v3, v10, v3
	v_lshl_add_u32 v3, v3, 2, 0
	v_cmp_gt_i32_e32 vcc, 64, v152
	s_waitcnt vmcnt(7)
	v_lshlrev_b32_e32 v17, 16, v17
	s_waitcnt vmcnt(6)
	v_lshlrev_b32_e32 v18, 16, v18
	s_waitcnt vmcnt(5)
	v_lshlrev_b32_e32 v8, 16, v8
	s_waitcnt vmcnt(4)
	v_lshlrev_b32_e32 v6, 16, v6
	v_mul_f32_e32 v5, v5, v17
	v_mul_f32_e32 v1, v1, v18
	v_mul_f32_e32 v8, v12, v8
	v_mul_f32_e32 v6, v14, v6
	ds_write2st64_b32 v11, v5, v1 offset1:32
	ds_write2st64_b32 v13, v8, v6 offset1:32
	v_exp_f32_e32 v1, v16
	s_waitcnt vmcnt(2)
	v_lshlrev_b32_e32 v8, 16, v9
	v_add_u32_e32 v5, 1, v10
	v_cvt_f32_i32_e32 v5, v5
	v_mul_f32_e32 v1, v1, v8
	v_sub_u32_e32 v8, 7, v10
	v_cvt_f32_i32_e32 v8, v8
	v_lshlrev_b32_e32 v7, 16, v7
	v_mul_f32_e32 v7, v15, v7
	v_lshl_add_u32 v6, v19, 2, 0
	v_mul_f32_e32 v5, v0, v5
	ds_write2st64_b32 v6, v7, v1 offset1:32
	s_waitcnt vmcnt(1)
	v_lshlrev_b32_e32 v1, 16, v4
	v_mul_f32_e32 v4, v0, v8
	v_mul_f32_e32 v5, 0x3fb8aa3b, v5
	v_mul_f32_e32 v4, 0x3fb8aa3b, v4
	v_exp_f32_e32 v5, v5
	v_exp_f32_e32 v4, v4
	s_waitcnt vmcnt(0)
	v_lshlrev_b32_e32 v2, 16, v2
	v_mul_f32_e32 v1, v5, v1
	v_mul_f32_e32 v2, v4, v2
	ds_write2st64_b32 v3, v1, v2 offset1:32
	s_waitcnt lgkmcnt(0)
	s_barrier
	v_mov_b32_e32 v246, v0
	v_mul_f32_e32 v0, 0x41000000, v0
	v_mul_f32_e32 v0, 0x3fb8aa3b, v0
	v_exp_f32_e32 v154, v0
	v_lshlrev_b32_e32 v0, 2, v152
	v_and_b32_e32 v205, 0x1fc, v0
	s_lshl_b32 s28, s0, 9
	v_or_b32_e32 v0, s28, v205
	v_ashrrev_i32_e32 v206, 7, v152
	v_ashrrev_i32_e32 v1, 31, v0
	v_lshlrev_b32_e32 v52, 6, v206
	v_lshl_add_u64 v[0:1], v[0:1], 4, s[38:39]
	s_ashr_i32 s1, s0, 31
	v_ashrrev_i32_e32 v53, 31, v52
	global_load_dwordx4 v[4:7], v[0:1], off
	global_load_dwordx4 v[40:43], v[0:1], off offset:16
	global_load_dwordx4 v[44:47], v[0:1], off offset:32
	global_load_dwordx4 v[48:51], v[0:1], off offset:48
	s_lshl_b64 s[14:15], s[0:1], 17
	v_lshlrev_b64 v[0:1], 9, v[52:53]
	v_lshl_add_u64 v[0:1], s[14:15], 0, v[0:1]
	v_or_b32_e32 v0, v0, v205
	v_lshl_add_u64 v[0:1], v[0:1], 2, s[44:45]
	v_add_co_u32_e32 v2, vcc, s24, v0
	global_load_dwordx4 v[36:39], v[0:1], off nt
	global_load_dwordx4 v[32:35], v[0:1], off offset:2048 nt
	v_addc_co_u32_e32 v3, vcc, 0, v1, vcc
	v_add_co_u32_e32 v24, vcc, s22, v0
	s_lshl_b64 s[0:1], s[0:1], 19
	s_nop 0
	v_addc_co_u32_e32 v25, vcc, 0, v1, vcc
	v_add_co_u32_e32 v0, vcc, s25, v0
	v_lshlrev_b64 v[52:53], 11, v[52:53]
	s_nop 0
	v_addc_co_u32_e32 v1, vcc, 0, v1, vcc
	global_load_dwordx4 v[16:19], v[24:25], off nt
	global_load_dwordx4 v[12:15], v[24:25], off offset:2048 nt
	global_load_dwordx4 v[20:23], v[2:3], off offset:2048 nt
	global_load_dwordx4 v[8:11], v[0:1], off nt
	global_load_dwordx4 v[28:31], v[24:25], off offset:-4096 nt
	s_nop 0
	global_load_dwordx4 v[0:3], v[0:1], off offset:2048 nt
	v_and_b32_e32 v27, 0x7f, v152
	v_lshl_add_u64 v[52:53], s[0:1], 0, v[52:53]
	v_cmp_gt_i32_e32 vcc, 64, v152
	s_nop 3
	s_and_saveexec_b64 s[14:15], vcc
	s_cbranch_execz .Lrs_a8_out
	v_ashrrev_i32_e32 v210, 3, v152
	v_and_b32_e32 v211, 7, v152
	v_cmp_le_i32_e32 vcc, v211, v210
	v_mov_b32_e32 v209, 0
	s_and_saveexec_b64 s[16:17], vcc
	s_cbranch_execz .Lrs_a8_in
	v_mul_f32_e32 v209, 0xc1000000, v246
	v_mul_f32_e32 v209, 0x3fb8aa3b, v209
	v_exp_f32_e32 v209, v209
	v_lshl_add_u32 v210, v210, 2, 0
	v_lshl_add_u32 v212, v211, 2, s23
	v_mov_b32_e32 v211, 0
	s_mov_b32 s1, 0
.Lrs_a8_loop:
	v_add_u32_e32 v213, s1, v210
	v_add_u32_e32 v244, s1, v212
	ds_read2_b32 v[214:215], v213 offset1:8
	ds_read2_b32 v[216:217], v244 offset1:8
	ds_read2_b32 v[218:219], v213 offset0:16 offset1:24
	ds_read2_b32 v[220:221], v244 offset0:16 offset1:24
	ds_read2_b32 v[222:223], v213 offset0:32 offset1:40
	ds_read2_b32 v[224:225], v244 offset0:32 offset1:40
	ds_read2_b32 v[226:227], v213 offset0:48 offset1:56
	ds_read2_b32 v[228:229], v244 offset0:48 offset1:56
	ds_read2_b32 v[230:231], v213 offset0:64 offset1:72
	ds_read2_b32 v[232:233], v244 offset0:64 offset1:72
	ds_read2_b32 v[234:235], v213 offset0:80 offset1:88
	ds_read2_b32 v[236:237], v244 offset0:80 offset1:88
	ds_read2_b32 v[238:239], v213 offset0:96 offset1:104
	ds_read2_b32 v[240:241], v244 offset0:96 offset1:104
	ds_read2_b32 v[242:243], v213 offset0:112 offset1:120
	ds_read2_b32 v[244:245], v244 offset0:112 offset1:120
	s_waitcnt lgkmcnt(14)
	v_fmac_f32_e32 v211, v214, v216
	v_fmac_f32_e32 v211, v215, v217
	s_waitcnt lgkmcnt(12)
	v_fmac_f32_e32 v211, v218, v220
	v_fmac_f32_e32 v211, v219, v221
	s_waitcnt lgkmcnt(10)
	v_fmac_f32_e32 v211, v222, v224
	v_fmac_f32_e32 v211, v223, v225
	s_waitcnt lgkmcnt(8)
	v_fmac_f32_e32 v211, v226, v228
	v_fmac_f32_e32 v211, v227, v229
	s_waitcnt lgkmcnt(6)
	v_fmac_f32_e32 v211, v230, v232
	v_fmac_f32_e32 v211, v231, v233
	s_waitcnt lgkmcnt(4)
	v_fmac_f32_e32 v211, v234, v236
	v_fmac_f32_e32 v211, v235, v237
	s_waitcnt lgkmcnt(2)
	v_fmac_f32_e32 v211, v238, v240
	v_fmac_f32_e32 v211, v239, v241
	s_addk_i32 s1, 0x200
	s_waitcnt lgkmcnt(0)
	v_fmac_f32_e32 v211, v242, v244
	s_cmpk_eq_i32 s1, 0x2000
	v_fmac_f32_e32 v211, v243, v245
	s_cbranch_scc0 .Lrs_a8_loop
	v_mul_f32_e32 v209, v209, v211
.Lrs_a8_in:
	s_or_b64 exec, exec, s[16:17]
	v_lshl_add_u32 v210, v152, 2, 0
	ds_write_b32 v210, v209 offset:16384
.Lrs_a8_out:
	s_waitcnt lgkmcnt(0)
	s_or_b64 exec, exec, s[14:15]
	v_mov_b32_e32 v24, 0
	v_lshl_or_b32 v52, v27, 4, v52
	s_mov_b32 s29, 0
	v_mov_b32_e32 v156, v154
	v_mov_b32_e32 v157, v154
	s_mov_b64 s[14:15], 0
	v_lshl_add_u32 v207, v206, 11, 0
	v_mov_b32_e32 v25, v24
	v_mov_b32_e32 v26, v24
	v_lshl_add_u64 v[158:159], s[92:93], 0, v[52:53]
	v_lshl_add_u64 v[160:161], s[44:45], 0, v[52:53]
	v_mov_b32_e32 v27, v24
	v_mov_b32_e32 v56, v24
	v_mov_b32_e32 v57, v24
	v_mov_b32_e32 v58, v24
	v_mov_b32_e32 v59, v24
	v_mov_b32_e32 v60, v24
	v_mov_b32_e32 v61, v24
	v_mov_b32_e32 v62, v24
	v_mov_b32_e32 v63, v24
	v_mov_b32_e32 v64, v24
	v_mov_b32_e32 v65, v24
	v_mov_b32_e32 v66, v24
	v_mov_b32_e32 v67, v24
	v_mov_b32_e32 v68, v24
	v_mov_b32_e32 v69, v24
	v_mov_b32_e32 v70, v24
	v_mov_b32_e32 v71, v24
	s_waitcnt vmcnt(11)
	v_lshlrev_b32_e32 v162, 16, v4
	v_and_b32_e32 v164, 0xffff0000, v4
	v_lshlrev_b32_e32 v166, 16, v5
	v_and_b32_e32 v168, 0xffff0000, v5
	v_lshlrev_b32_e32 v170, 16, v6
	v_and_b32_e32 v172, 0xffff0000, v6
	v_lshlrev_b32_e32 v174, 16, v7
	v_and_b32_e32 v176, 0xffff0000, v7
	s_waitcnt vmcnt(10)
	v_lshlrev_b32_e32 v163, 16, v40
	v_and_b32_e32 v165, 0xffff0000, v40
	s_waitcnt vmcnt(7)
	v_mov_b64_e32 v[4:5], v[36:37]
	v_lshlrev_b32_e32 v167, 16, v41
	v_and_b32_e32 v169, 0xffff0000, v41
	v_lshlrev_b32_e32 v171, 16, v42
	v_and_b32_e32 v173, 0xffff0000, v42
	v_lshlrev_b32_e32 v175, 16, v43
	v_and_b32_e32 v177, 0xffff0000, v43
	v_lshlrev_b32_e32 v178, 16, v44
	v_and_b32_e32 v180, 0xffff0000, v44
	v_lshlrev_b32_e32 v182, 16, v45
	v_and_b32_e32 v184, 0xffff0000, v45
	v_lshlrev_b32_e32 v186, 16, v46
	v_and_b32_e32 v188, 0xffff0000, v46
	v_lshlrev_b32_e32 v190, 16, v47
	v_and_b32_e32 v192, 0xffff0000, v47
	v_lshlrev_b32_e32 v179, 16, v48
	v_and_b32_e32 v181, 0xffff0000, v48
	v_lshlrev_b32_e32 v183, 16, v49
	v_and_b32_e32 v185, 0xffff0000, v49
	v_lshlrev_b32_e32 v187, 16, v50
	v_and_b32_e32 v189, 0xffff0000, v50
	v_lshlrev_b32_e32 v191, 16, v51
	v_and_b32_e32 v193, 0xffff0000, v51
	v_mov_b32_e32 v40, v24
	v_mov_b32_e32 v41, v24
	v_mov_b32_e32 v42, v24
	v_mov_b32_e32 v43, v24
	v_mov_b32_e32 v44, v24
	v_mov_b32_e32 v45, v24
	v_mov_b32_e32 v46, v24
	v_mov_b32_e32 v47, v24
	v_mov_b32_e32 v48, v24
	v_mov_b32_e32 v49, v24
	v_mov_b32_e32 v50, v24
	v_mov_b32_e32 v51, v24
	v_mov_b64_e32 v[6:7], v[38:39]
	s_branch .LBB0_1347
